# hand-written W_o residual epilogue: row loads three row groups ahead
# baseline (speedup 1.0000x reference)
; DI const float* modp(const Frame& F, int l, int mr, int which) { return (const float*)(F.ws + WS_MOD) + ((size_t)(l * 9 + mr) * 6 + which) * 1024; }
;     DI void operator()(Acc& acc, const Unit& u, int wr, int wc, int fr, int fq) const {
;         const int row0 = u.pm * 256, col0 = u.pn * 256;
;         const float* g = modp(F, F.l, modrow_of_tile(row0), which) + col0;
;         const bool ln = (lnmode != 0) && row0 < ML;
;         const float* st = (const float*)(F.ws + (lnmode == 1 ? WS_ST1 : WS_ST2));
;         const float* lg = lnmode == 1 ? pin(F, I_LN1G) + F.l * 1024 : pin(F, I_LN2G) + (F.l > 0 ? F.l - 1 : 0) * 1024;
;         const float* lb = lnmode == 1 ? pin(F, I_LN1B) + F.l * 1024 : pin(F, I_LN2B) + (F.l > 0 ? F.l - 1 : 0) * 1024;
;         {
; #pragma unroll
;             for (int bj = 0; bj < 2; ++bj) {
;                 f32x4 gv0 = *(const f32x4*)(g + EPI_COL8(bj)), gv1 = *(const f32x4*)(g + EPI_COL8(bj) + 4);
;                 f32x4 c0 = {0.f, 0.f, 0.f, 0.f}, c1 = {0.f, 0.f, 0.f, 0.f};
;                 if (ln) { c0 = *(const f32x4*)(lb + col0 + EPI_COL8(bj)) * ALPHA; c1 = *(const f32x4*)(lb + col0 + EPI_COL8(bj) + 4) * ALPHA; }
; #pragma unroll
;                 for (int ai = 0; ai < 2; ++ai)
; #pragma unroll
;                     for (int m = 0; m < 4; ++m) { acc[ai][bj][m][0] = acc[ai][bj][m][0] * gv0 + c0; acc[ai][bj][m][1] = acc[ai][bj][m][1] * gv1 + c1; }
;             }
;         }
;         f32x4 la[2][2];
; #pragma unroll
;         for (int bj = 0; bj < 2; ++bj) {
; #pragma unroll
;             for (int n = 0; n < 2; ++n) la[bj][n] = (f32x4){ALPHA, ALPHA, ALPHA, ALPHA};
;             if (ln) {
; #pragma unroll
;                 for (int n = 0; n < 2; ++n) la[bj][n] = *(const f32x4*)(lg + col0 + EPI_COL8(bj) + 4 * n) * ALPHA; } }
;         const float* xib = (from_input ? xin_ptr(F, row0) : xrow_ptr(F, row0)) + col0; float* xob = xrow_ptr(F, row0) + col0;
;         int oz_ = 0; asm volatile("" : "+v"(oz_));
; #pragma unroll
;         for (int aim = 0; aim < 8; ++aim) { const int ai = aim >> 2, m = aim & 3;
;             f32x4 xa[2][2]; f32x2 sv = {0.f, 1.f};
;             if (ln) sv = *(const f32x2*)(st + 2 * (size_t)(row0 + EPI_ROWS(ai, m) + oz_));
.LBB0_142:
	v_readlane_b32 s24, v255, 35
	v_readlane_b32 s26, v255, 24
	v_readlane_b32 s27, v255, 25
	s_lshl_b32 s56, s4, 8
	s_lshl_b32 s57, s16, 10
	s_cmp_lt_u32 s4, 64
	s_cselect_b32 s25, 1, 0
	s_load_dwordx2 s[10:11], s[26:27], 0x0
	s_load_dwordx2 s[40:41], s[26:27], 0x10
	s_load_dwordx4 s[12:15], s[26:27], 0xb8
	s_min_u32 s5, s56, 0x4000
	s_lshr_b32 s5, s5, 11
	s_mul_i32 s8, s24, 9
	s_add_i32 s5, s5, s8
	s_mul_i32 s5, s5, 0x6000
	s_add_u32 s8, s94, s5
	s_addc_u32 s9, s95, 0
	s_add_u32 s8, s8, 0x102000
	s_addc_u32 s9, s9, 0
	s_add_u32 s8, s8, s57
	s_addc_u32 s9, s9, 0
	global_load_dwordx4 v[64:67], v96, s[8:9]
	global_load_dwordx4 v[68:71], v96, s[8:9] offset:16
	global_load_dwordx4 v[72:75], v96, s[8:9] offset:512
	global_load_dwordx4 v[76:79], v96, s[8:9] offset:528
	v_lshlrev_b32_e32 v206, 12, v207
	v_add_u32_e32 v206, v206, v96
	v_lshlrev_b32_e32 v208, 3, v207
	v_readlane_b32 s34, v255, 17
	v_readlane_b32 s35, v255, 18
	s_lshl_b32 s5, s56, 12
	s_add_u32 s34, s34, s5
	s_addc_u32 s35, s35, 0
	s_sub_u32 s5, s5, 0x4000000
	s_add_u32 s16, s94, 0x3600000
	s_addc_u32 s101, s95, 0
	s_add_u32 s16, s16, s5
	s_addc_u32 s101, s101, 0
	s_cmp_eq_u32 s25, 1
	s_cselect_b32 s34, s34, s16
	s_cselect_b32 s35, s35, s101
	s_add_u32 s34, s34, s57
	s_addc_u32 s35, s35, 0
	s_waitcnt lgkmcnt(0)
	s_lshl_b32 s16, s56, 12
	s_add_u32 s10, s10, s16
	s_addc_u32 s11, s11, 0
	s_add_u32 s40, s40, s5
	s_addc_u32 s41, s41, 0
	s_cmp_eq_u32 s25, 1
	s_cselect_b32 s10, s10, s40
	s_cselect_b32 s11, s11, s41
	s_add_u32 s10, s10, s57
	s_addc_u32 s11, s11, 0
	s_cmp_eq_u32 s24, 0
	s_cselect_b32 s10, s10, s34
	s_cselect_b32 s11, s11, s35
	global_load_dwordx4 v[188:191], v206, s[10:11]
	global_load_dwordx4 v[192:195], v206, s[10:11] offset:16
	global_load_dwordx4 v[196:199], v206, s[10:11] offset:512
	global_load_dwordx4 v[200:203], v206, s[10:11] offset:528
	s_cmp_gt_u32 s24, 0
	s_cselect_b32 s5, s25, 0
	s_cmp_eq_u32 s5, 1
	s_cbranch_scc0 .Lres_o_noln
	s_add_i32 s5, s24, -1
	s_lshl_b32 s5, s5, 12
	s_add_u32 s5, s5, s57
	s_add_u32 s12, s12, s5
	s_addc_u32 s13, s13, 0
	s_add_u32 s14, s14, s5
	s_addc_u32 s15, s15, 0
	global_load_dwordx4 v[158:161], v96, s[14:15]
	global_load_dwordx4 v[162:165], v96, s[14:15] offset:16
	global_load_dwordx4 v[166:169], v96, s[14:15] offset:512
	global_load_dwordx4 v[170:173], v96, s[14:15] offset:528
	global_load_dwordx4 v[228:231], v96, s[12:13]
	global_load_dwordx4 v[232:235], v96, s[12:13] offset:16
	global_load_dwordx4 v[236:239], v96, s[12:13] offset:512
	global_load_dwordx4 v[240:243], v96, s[12:13] offset:528
	s_lshl_b32 s5, s56, 3
	s_add_u32 s8, s94, s5
	s_addc_u32 s9, s95, 0
	s_add_u32 s8, s8, 0x4c0000
	s_addc_u32 s9, s9, 0
	global_load_dwordx2 v[244:245], v208, s[8:9]
	global_load_dwordx2 v[246:247], v208, s[8:9] offset:128
	global_load_dwordx2 v[248:249], v208, s[8:9] offset:256
	global_load_dwordx2 v[250:251], v208, s[8:9] offset:384
	global_load_dwordx2 v[252:253], v208, s[8:9] offset:1024
	global_load_dwordx2 v[174:175], v208, s[8:9] offset:1152
	global_load_dwordx2 v[176:177], v208, s[8:9] offset:1280
	global_load_dwordx2 v[204:205], v208, s[8:9] offset:1408
	s_waitcnt vmcnt(0)
	v_mul_f32_e32 v158, 0x3fd744fd, v158
	v_mul_f32_e32 v159, 0x3fd744fd, v159
	v_mul_f32_e32 v160, 0x3fd744fd, v160
	v_mul_f32_e32 v161, 0x3fd744fd, v161
	v_mul_f32_e32 v162, 0x3fd744fd, v162
	v_mul_f32_e32 v163, 0x3fd744fd, v163
	v_mul_f32_e32 v164, 0x3fd744fd, v164
	v_mul_f32_e32 v165, 0x3fd744fd, v165
	v_mul_f32_e32 v166, 0x3fd744fd, v166
	v_mul_f32_e32 v167, 0x3fd744fd, v167
	v_mul_f32_e32 v168, 0x3fd744fd, v168
	v_mul_f32_e32 v169, 0x3fd744fd, v169
	v_mul_f32_e32 v170, 0x3fd744fd, v170
	v_mul_f32_e32 v171, 0x3fd744fd, v171
	v_mul_f32_e32 v172, 0x3fd744fd, v172
	v_mul_f32_e32 v173, 0x3fd744fd, v173
	v_mul_f32_e32 v228, 0x3fd744fd, v228
	v_mul_f32_e32 v229, 0x3fd744fd, v229
	v_mul_f32_e32 v230, 0x3fd744fd, v230
	v_mul_f32_e32 v231, 0x3fd744fd, v231
	v_mul_f32_e32 v232, 0x3fd744fd, v232
	v_mul_f32_e32 v233, 0x3fd744fd, v233
	v_mul_f32_e32 v234, 0x3fd744fd, v234
	v_mul_f32_e32 v235, 0x3fd744fd, v235
	v_mul_f32_e32 v236, 0x3fd744fd, v236
	v_mul_f32_e32 v237, 0x3fd744fd, v237
	v_mul_f32_e32 v238, 0x3fd744fd, v238
	v_mul_f32_e32 v239, 0x3fd744fd, v239
	v_mul_f32_e32 v240, 0x3fd744fd, v240
	v_mul_f32_e32 v241, 0x3fd744fd, v241
	v_mul_f32_e32 v242, 0x3fd744fd, v242
	v_mul_f32_e32 v243, 0x3fd744fd, v243
	s_branch .Lres_o_fold
.Lres_o_noln:
	v_mov_b32_e32 v158, 0
	v_mov_b32_e32 v159, 0
	v_mov_b32_e32 v160, 0
	v_mov_b32_e32 v161, 0
	v_mov_b32_e32 v162, 0
	v_mov_b32_e32 v163, 0
	v_mov_b32_e32 v164, 0
	v_mov_b32_e32 v165, 0
	v_mov_b32_e32 v166, 0
	v_mov_b32_e32 v167, 0
	v_mov_b32_e32 v168, 0
	v_mov_b32_e32 v169, 0
	v_mov_b32_e32 v170, 0
	v_mov_b32_e32 v171, 0
	v_mov_b32_e32 v172, 0
	v_mov_b32_e32 v173, 0
	v_mov_b32_e32 v228, 0x3fd744fd
	v_mov_b32_e32 v229, 0x3fd744fd
	v_mov_b32_e32 v230, 0x3fd744fd
	v_mov_b32_e32 v231, 0x3fd744fd
	v_mov_b32_e32 v232, 0x3fd744fd
	v_mov_b32_e32 v233, 0x3fd744fd
	v_mov_b32_e32 v234, 0x3fd744fd
	v_mov_b32_e32 v235, 0x3fd744fd
	v_mov_b32_e32 v236, 0x3fd744fd
	v_mov_b32_e32 v237, 0x3fd744fd
	v_mov_b32_e32 v238, 0x3fd744fd
	v_mov_b32_e32 v239, 0x3fd744fd
	v_mov_b32_e32 v240, 0x3fd744fd
	v_mov_b32_e32 v241, 0x3fd744fd
	v_mov_b32_e32 v242, 0x3fd744fd
	v_mov_b32_e32 v243, 0x3fd744fd
	v_mov_b32_e32 v244, 0
	v_mov_b32_e32 v245, 1.0
	v_mov_b32_e32 v246, 0
	v_mov_b32_e32 v247, 1.0
	v_mov_b32_e32 v248, 0
	v_mov_b32_e32 v249, 1.0
	v_mov_b32_e32 v250, 0
	v_mov_b32_e32 v251, 1.0
	v_mov_b32_e32 v252, 0
	v_mov_b32_e32 v253, 1.0
	v_mov_b32_e32 v174, 0
	v_mov_b32_e32 v175, 1.0
	v_mov_b32_e32 v176, 0
	v_mov_b32_e32 v177, 1.0
	v_mov_b32_e32 v204, 0
	v_mov_b32_e32 v205, 1.0
	s_waitcnt vmcnt(4)
;     DI void operator()(Acc& acc, const Unit& u, int wr, int wc, int fr, int fq) const {
;     ...
;                 for (int ai = 0; ai < 2; ++ai)
; #pragma unroll
;                     for (int m = 0; m < 4; ++m) { acc[ai][bj][m][0] = acc[ai][bj][m][0] * gv0 + c0; acc[ai][bj][m][1] = acc[ai][bj][m][1] * gv1 + c1; }
;             }
;         }
;         f32x4 la[2][2];
; #pragma unroll
;         for (int bj = 0; bj < 2; ++bj) {
; #pragma unroll
;             for (int n = 0; n < 2; ++n) la[bj][n] = (f32x4){ALPHA, ALPHA, ALPHA, ALPHA};
;             if (ln) {
; #pragma unroll
;                 for (int n = 0; n < 2; ++n) la[bj][n] = *(const f32x4*)(lg + col0 + EPI_COL8(bj) + 4 * n) * ALPHA; } }
;         const float* xib = (from_input ? xin_ptr(F, row0) : xrow_ptr(F, row0)) + col0; float* xob = xrow_ptr(F, row0) + col0;
;         int oz_ = 0; asm volatile("" : "+v"(oz_));
; #pragma unroll
;         for (int aim = 0; aim < 8; ++aim) { const int ai = aim >> 2, m = aim & 3;
;             f32x4 xa[2][2]; f32x2 sv = {0.f, 1.f};
;             if (ln) sv = *(const f32x2*)(st + 2 * (size_t)(row0 + EPI_ROWS(ai, m) + oz_));
; #pragma unroll
;             for (int bj = 0; bj < 2; ++bj) { const float* p = xib + (size_t)(EPI_ROWS(ai, m) + oz_) * D + EPI_COL8(bj); xa[bj][0] = *(const f32x4*)p; xa[bj][1] = *(const f32x4*)(p + 4); }
; #pragma unroll
;             for (int bj = 0; bj < 2; ++bj) { float* p = xob + (size_t)(EPI_ROWS(ai, m) + oz_) * D + EPI_COL8(bj);
;                 *(f32x4*)p = ((xa[bj][0] - sv[0]) * sv[1]) * la[bj][0] + acc[ai][bj][m][0];
;                 *(f32x4*)(p + 4) = ((xa[bj][1] - sv[0]) * sv[1]) * la[bj][1] + acc[ai][bj][m][1]; }
.Lres_o_fold:
	v_pk_fma_f32 v[134:135], v[134:135], v[64:65], v[158:159]
	v_pk_fma_f32 v[136:137], v[136:137], v[66:67], v[160:161]
	v_pk_fma_f32 v[118:119], v[118:119], v[64:65], v[158:159]
	v_pk_fma_f32 v[120:121], v[120:121], v[66:67], v[160:161]
	v_pk_fma_f32 v[102:103], v[102:103], v[64:65], v[158:159]
	v_pk_fma_f32 v[104:105], v[104:105], v[66:67], v[160:161]
	v_pk_fma_f32 v[84:85], v[84:85], v[64:65], v[158:159]
	v_pk_fma_f32 v[86:87], v[86:87], v[66:67], v[160:161]
	v_pk_fma_f32 v[52:53], v[52:53], v[64:65], v[158:159]
	v_pk_fma_f32 v[54:55], v[54:55], v[66:67], v[160:161]
	v_pk_fma_f32 v[36:37], v[36:37], v[64:65], v[158:159]
	v_pk_fma_f32 v[38:39], v[38:39], v[66:67], v[160:161]
	v_pk_fma_f32 v[20:21], v[20:21], v[64:65], v[158:159]
	v_pk_fma_f32 v[22:23], v[22:23], v[66:67], v[160:161]
	v_pk_fma_f32 v[8:9], v[8:9], v[64:65], v[158:159]
	v_pk_fma_f32 v[10:11], v[10:11], v[66:67], v[160:161]
	v_pk_fma_f32 v[130:131], v[130:131], v[68:69], v[162:163]
	v_pk_fma_f32 v[132:133], v[132:133], v[70:71], v[164:165]
	v_pk_fma_f32 v[114:115], v[114:115], v[68:69], v[162:163]
	v_pk_fma_f32 v[116:117], v[116:117], v[70:71], v[164:165]
	v_pk_fma_f32 v[98:99], v[98:99], v[68:69], v[162:163]
	v_pk_fma_f32 v[100:101], v[100:101], v[70:71], v[164:165]
	v_pk_fma_f32 v[80:81], v[80:81], v[68:69], v[162:163]
	v_pk_fma_f32 v[82:83], v[82:83], v[70:71], v[164:165]
	v_pk_fma_f32 v[48:49], v[48:49], v[68:69], v[162:163]
	v_pk_fma_f32 v[50:51], v[50:51], v[70:71], v[164:165]
	v_pk_fma_f32 v[32:33], v[32:33], v[68:69], v[162:163]
	v_pk_fma_f32 v[34:35], v[34:35], v[70:71], v[164:165]
	v_pk_fma_f32 v[16:17], v[16:17], v[68:69], v[162:163]
	v_pk_fma_f32 v[18:19], v[18:19], v[70:71], v[164:165]
	v_pk_fma_f32 v[4:5], v[4:5], v[68:69], v[162:163]
	v_pk_fma_f32 v[6:7], v[6:7], v[70:71], v[164:165]
	v_pk_fma_f32 v[142:143], v[142:143], v[72:73], v[166:167]
	v_pk_fma_f32 v[144:145], v[144:145], v[74:75], v[168:169]
	v_pk_fma_f32 v[126:127], v[126:127], v[72:73], v[166:167]
	v_pk_fma_f32 v[128:129], v[128:129], v[74:75], v[168:169]
	v_pk_fma_f32 v[110:111], v[110:111], v[72:73], v[166:167]
	v_pk_fma_f32 v[112:113], v[112:113], v[74:75], v[168:169]
	v_pk_fma_f32 v[92:93], v[92:93], v[72:73], v[166:167]
	v_pk_fma_f32 v[94:95], v[94:95], v[74:75], v[168:169]
	v_pk_fma_f32 v[60:61], v[60:61], v[72:73], v[166:167]
	v_pk_fma_f32 v[62:63], v[62:63], v[74:75], v[168:169]
	v_pk_fma_f32 v[44:45], v[44:45], v[72:73], v[166:167]
	v_pk_fma_f32 v[46:47], v[46:47], v[74:75], v[168:169]
	v_pk_fma_f32 v[28:29], v[28:29], v[72:73], v[166:167]
	v_pk_fma_f32 v[30:31], v[30:31], v[74:75], v[168:169]
	v_pk_fma_f32 v[12:13], v[12:13], v[72:73], v[166:167]
	v_pk_fma_f32 v[14:15], v[14:15], v[74:75], v[168:169]
	v_pk_fma_f32 v[138:139], v[138:139], v[76:77], v[170:171]
	v_pk_fma_f32 v[140:141], v[140:141], v[78:79], v[172:173]
	v_pk_fma_f32 v[122:123], v[122:123], v[76:77], v[170:171]
	v_pk_fma_f32 v[124:125], v[124:125], v[78:79], v[172:173]
	v_pk_fma_f32 v[106:107], v[106:107], v[76:77], v[170:171]
	v_pk_fma_f32 v[108:109], v[108:109], v[78:79], v[172:173]
	v_pk_fma_f32 v[88:89], v[88:89], v[76:77], v[170:171]
	v_pk_fma_f32 v[90:91], v[90:91], v[78:79], v[172:173]
	v_pk_fma_f32 v[56:57], v[56:57], v[76:77], v[170:171]
	v_pk_fma_f32 v[58:59], v[58:59], v[78:79], v[172:173]
	v_pk_fma_f32 v[40:41], v[40:41], v[76:77], v[170:171]
	v_pk_fma_f32 v[42:43], v[42:43], v[78:79], v[172:173]
	v_pk_fma_f32 v[24:25], v[24:25], v[76:77], v[170:171]
	v_pk_fma_f32 v[26:27], v[26:27], v[78:79], v[172:173]
	v_pk_fma_f32 v[0:1], v[0:1], v[76:77], v[170:171]
	v_pk_fma_f32 v[2:3], v[2:3], v[78:79], v[172:173]
	s_add_u32 s40, s10, 0x10000
	s_addc_u32 s41, s11, 0
	global_load_dwordx4 v[64:67], v206, s[40:41]
	global_load_dwordx4 v[68:71], v206, s[40:41] offset:16
	global_load_dwordx4 v[72:75], v206, s[40:41] offset:512
	global_load_dwordx4 v[76:79], v206, s[40:41] offset:528
	s_add_u32 s40, s10, 0x20000
	s_addc_u32 s41, s11, 0
	global_load_dwordx4 v[158:161], v206, s[40:41]
	global_load_dwordx4 v[162:165], v206, s[40:41] offset:16
	global_load_dwordx4 v[166:169], v206, s[40:41] offset:512
	global_load_dwordx4 v[170:173], v206, s[40:41] offset:528
	s_mov_b64 s[12:13], s[34:35]
	s_waitcnt vmcnt(8)
	v_sub_f32_e32 v188, v188, v244
	v_sub_f32_e32 v189, v189, v244
	v_sub_f32_e32 v190, v190, v244
	v_sub_f32_e32 v191, v191, v244
	v_sub_f32_e32 v192, v192, v244
	v_sub_f32_e32 v193, v193, v244
	v_sub_f32_e32 v194, v194, v244
	v_sub_f32_e32 v195, v195, v244
	v_sub_f32_e32 v196, v196, v244
	v_sub_f32_e32 v197, v197, v244
	v_sub_f32_e32 v198, v198, v244
	v_sub_f32_e32 v199, v199, v244
	v_sub_f32_e32 v200, v200, v244
	v_sub_f32_e32 v201, v201, v244
	v_sub_f32_e32 v202, v202, v244
	v_sub_f32_e32 v203, v203, v244
	v_pk_mul_f32 v[188:189], v[244:245], v[188:189] op_sel:[1,0]
	v_pk_mul_f32 v[190:191], v[244:245], v[190:191] op_sel:[1,0]
	v_pk_mul_f32 v[192:193], v[244:245], v[192:193] op_sel:[1,0]
	v_pk_mul_f32 v[194:195], v[244:245], v[194:195] op_sel:[1,0]
	v_pk_mul_f32 v[196:197], v[244:245], v[196:197] op_sel:[1,0]
	v_pk_mul_f32 v[198:199], v[244:245], v[198:199] op_sel:[1,0]
	v_pk_mul_f32 v[200:201], v[244:245], v[200:201] op_sel:[1,0]
	v_pk_mul_f32 v[202:203], v[244:245], v[202:203] op_sel:[1,0]
	v_pk_fma_f32 v[188:189], v[228:229], v[188:189], v[134:135]
	v_pk_fma_f32 v[190:191], v[230:231], v[190:191], v[136:137]
	v_pk_fma_f32 v[192:193], v[232:233], v[192:193], v[130:131]
	v_pk_fma_f32 v[194:195], v[234:235], v[194:195], v[132:133]
	v_pk_fma_f32 v[196:197], v[236:237], v[196:197], v[142:143]
	v_pk_fma_f32 v[198:199], v[238:239], v[198:199], v[144:145]
	v_pk_fma_f32 v[200:201], v[240:241], v[200:201], v[138:139]
	v_pk_fma_f32 v[202:203], v[242:243], v[202:203], v[140:141]
	global_store_dwordx4 v206, v[188:191], s[12:13]
	global_store_dwordx4 v206, v[192:195], s[12:13] offset:16
	global_store_dwordx4 v206, v[196:199], s[12:13] offset:512
	global_store_dwordx4 v206, v[200:203], s[12:13] offset:528
	s_add_u32 s40, s10, 0x30000
	s_addc_u32 s41, s11, 0
	global_load_dwordx4 v[134:137], v206, s[40:41]
	global_load_dwordx4 v[130:133], v206, s[40:41] offset:16
	global_load_dwordx4 v[142:145], v206, s[40:41] offset:512
	global_load_dwordx4 v[138:141], v206, s[40:41] offset:528
	s_waitcnt vmcnt(12)
; #define ROW_FENCE asm volatile("" ::: "memory")
;     DI void operator()(Acc& acc, const Unit& u, int wr, int wc, int fr, int fq) const {
;     ...
;         for (int aim = 0; aim < 8; ++aim) { const int ai = aim >> 2, m = aim & 3;
;             f32x4 xa[2][2]; f32x2 sv = {0.f, 1.f};
;             if (ln) sv = *(const f32x2*)(st + 2 * (size_t)(row0 + EPI_ROWS(ai, m) + oz_));
; #pragma unroll
;             for (int bj = 0; bj < 2; ++bj) { const float* p = xib + (size_t)(EPI_ROWS(ai, m) + oz_) * D + EPI_COL8(bj); xa[bj][0] = *(const f32x4*)p; xa[bj][1] = *(const f32x4*)(p + 4); }
; #pragma unroll
;             for (int bj = 0; bj < 2; ++bj) { float* p = xob + (size_t)(EPI_ROWS(ai, m) + oz_) * D + EPI_COL8(bj);
;                 *(f32x4*)p = ((xa[bj][0] - sv[0]) * sv[1]) * la[bj][0] + acc[ai][bj][m][0];
;                 *(f32x4*)(p + 4) = ((xa[bj][1] - sv[0]) * sv[1]) * la[bj][1] + acc[ai][bj][m][1]; }
;             if (m & 1) ROW_FENCE;
;         }
	v_sub_f32_e32 v64, v64, v246
	v_sub_f32_e32 v65, v65, v246
	v_sub_f32_e32 v66, v66, v246
	v_sub_f32_e32 v67, v67, v246
	v_sub_f32_e32 v68, v68, v246
	v_sub_f32_e32 v69, v69, v246
	v_sub_f32_e32 v70, v70, v246
	v_sub_f32_e32 v71, v71, v246
	v_sub_f32_e32 v72, v72, v246
	v_sub_f32_e32 v73, v73, v246
	v_sub_f32_e32 v74, v74, v246
	v_sub_f32_e32 v75, v75, v246
	v_sub_f32_e32 v76, v76, v246
	v_sub_f32_e32 v77, v77, v246
	v_sub_f32_e32 v78, v78, v246
	v_sub_f32_e32 v79, v79, v246
	v_pk_mul_f32 v[64:65], v[246:247], v[64:65] op_sel:[1,0]
	v_pk_mul_f32 v[66:67], v[246:247], v[66:67] op_sel:[1,0]
	v_pk_mul_f32 v[68:69], v[246:247], v[68:69] op_sel:[1,0]
	v_pk_mul_f32 v[70:71], v[246:247], v[70:71] op_sel:[1,0]
	v_pk_mul_f32 v[72:73], v[246:247], v[72:73] op_sel:[1,0]
	v_pk_mul_f32 v[74:75], v[246:247], v[74:75] op_sel:[1,0]
	v_pk_mul_f32 v[76:77], v[246:247], v[76:77] op_sel:[1,0]
	v_pk_mul_f32 v[78:79], v[246:247], v[78:79] op_sel:[1,0]
	v_pk_fma_f32 v[64:65], v[228:229], v[64:65], v[118:119]
	v_pk_fma_f32 v[66:67], v[230:231], v[66:67], v[120:121]
	v_pk_fma_f32 v[68:69], v[232:233], v[68:69], v[114:115]
	v_pk_fma_f32 v[70:71], v[234:235], v[70:71], v[116:117]
	v_pk_fma_f32 v[72:73], v[236:237], v[72:73], v[126:127]
	v_pk_fma_f32 v[74:75], v[238:239], v[74:75], v[128:129]
	v_pk_fma_f32 v[76:77], v[240:241], v[76:77], v[122:123]
	v_pk_fma_f32 v[78:79], v[242:243], v[78:79], v[124:125]
	s_add_u32 s14, s12, 0x10000
	s_addc_u32 s15, s13, 0
	global_store_dwordx4 v206, v[64:67], s[14:15]
	global_store_dwordx4 v206, v[68:71], s[14:15] offset:16
	global_store_dwordx4 v206, v[72:75], s[14:15] offset:512
	global_store_dwordx4 v206, v[76:79], s[14:15] offset:528
	s_add_u32 s40, s10, 0x80000
	s_addc_u32 s41, s11, 0
	global_load_dwordx4 v[118:121], v206, s[40:41]
	global_load_dwordx4 v[114:117], v206, s[40:41] offset:16
	global_load_dwordx4 v[126:129], v206, s[40:41] offset:512
	global_load_dwordx4 v[122:125], v206, s[40:41] offset:528
	s_waitcnt vmcnt(16)
	v_sub_f32_e32 v158, v158, v248
	v_sub_f32_e32 v159, v159, v248
	v_sub_f32_e32 v160, v160, v248
	v_sub_f32_e32 v161, v161, v248
	v_sub_f32_e32 v162, v162, v248
	v_sub_f32_e32 v163, v163, v248
	v_sub_f32_e32 v164, v164, v248
	v_sub_f32_e32 v165, v165, v248
	v_sub_f32_e32 v166, v166, v248
	v_sub_f32_e32 v167, v167, v248
	v_sub_f32_e32 v168, v168, v248
	v_sub_f32_e32 v169, v169, v248
	v_sub_f32_e32 v170, v170, v248
	v_sub_f32_e32 v171, v171, v248
	v_sub_f32_e32 v172, v172, v248
	v_sub_f32_e32 v173, v173, v248
	v_pk_mul_f32 v[158:159], v[248:249], v[158:159] op_sel:[1,0]
	v_pk_mul_f32 v[160:161], v[248:249], v[160:161] op_sel:[1,0]
	v_pk_mul_f32 v[162:163], v[248:249], v[162:163] op_sel:[1,0]
	v_pk_mul_f32 v[164:165], v[248:249], v[164:165] op_sel:[1,0]
	v_pk_mul_f32 v[166:167], v[248:249], v[166:167] op_sel:[1,0]
	v_pk_mul_f32 v[168:169], v[248:249], v[168:169] op_sel:[1,0]
	v_pk_mul_f32 v[170:171], v[248:249], v[170:171] op_sel:[1,0]
	v_pk_mul_f32 v[172:173], v[248:249], v[172:173] op_sel:[1,0]
	v_pk_fma_f32 v[158:159], v[228:229], v[158:159], v[102:103]
	v_pk_fma_f32 v[160:161], v[230:231], v[160:161], v[104:105]
	v_pk_fma_f32 v[162:163], v[232:233], v[162:163], v[98:99]
	v_pk_fma_f32 v[164:165], v[234:235], v[164:165], v[100:101]
	v_pk_fma_f32 v[166:167], v[236:237], v[166:167], v[110:111]
	v_pk_fma_f32 v[168:169], v[238:239], v[168:169], v[112:113]
	v_pk_fma_f32 v[170:171], v[240:241], v[170:171], v[106:107]
	v_pk_fma_f32 v[172:173], v[242:243], v[172:173], v[108:109]
	s_add_u32 s14, s12, 0x20000
	s_addc_u32 s15, s13, 0
	global_store_dwordx4 v206, v[158:161], s[14:15]
	global_store_dwordx4 v206, v[162:165], s[14:15] offset:16
	global_store_dwordx4 v206, v[166:169], s[14:15] offset:512
	global_store_dwordx4 v206, v[170:173], s[14:15] offset:528
	s_add_u32 s40, s10, 0x90000
	s_addc_u32 s41, s11, 0
	global_load_dwordx4 v[102:105], v206, s[40:41]
	global_load_dwordx4 v[98:101], v206, s[40:41] offset:16
	global_load_dwordx4 v[110:113], v206, s[40:41] offset:512
	global_load_dwordx4 v[106:109], v206, s[40:41] offset:528
	s_waitcnt vmcnt(16)
	v_sub_f32_e32 v134, v134, v250
	v_sub_f32_e32 v135, v135, v250
	v_sub_f32_e32 v136, v136, v250
	v_sub_f32_e32 v137, v137, v250
	v_sub_f32_e32 v130, v130, v250
	v_sub_f32_e32 v131, v131, v250
	v_sub_f32_e32 v132, v132, v250
	v_sub_f32_e32 v133, v133, v250
	v_sub_f32_e32 v142, v142, v250
	v_sub_f32_e32 v143, v143, v250
	v_sub_f32_e32 v144, v144, v250
	v_sub_f32_e32 v145, v145, v250
	v_sub_f32_e32 v138, v138, v250
	v_sub_f32_e32 v139, v139, v250
	v_sub_f32_e32 v140, v140, v250
	v_sub_f32_e32 v141, v141, v250
	v_pk_mul_f32 v[134:135], v[250:251], v[134:135] op_sel:[1,0]
	v_pk_mul_f32 v[136:137], v[250:251], v[136:137] op_sel:[1,0]
	v_pk_mul_f32 v[130:131], v[250:251], v[130:131] op_sel:[1,0]
	v_pk_mul_f32 v[132:133], v[250:251], v[132:133] op_sel:[1,0]
	v_pk_mul_f32 v[142:143], v[250:251], v[142:143] op_sel:[1,0]
	v_pk_mul_f32 v[144:145], v[250:251], v[144:145] op_sel:[1,0]
	v_pk_mul_f32 v[138:139], v[250:251], v[138:139] op_sel:[1,0]
	v_pk_mul_f32 v[140:141], v[250:251], v[140:141] op_sel:[1,0]
	v_pk_fma_f32 v[134:135], v[228:229], v[134:135], v[84:85]
	v_pk_fma_f32 v[136:137], v[230:231], v[136:137], v[86:87]
	v_pk_fma_f32 v[130:131], v[232:233], v[130:131], v[80:81]
	v_pk_fma_f32 v[132:133], v[234:235], v[132:133], v[82:83]
	v_pk_fma_f32 v[142:143], v[236:237], v[142:143], v[92:93]
	v_pk_fma_f32 v[144:145], v[238:239], v[144:145], v[94:95]
	v_pk_fma_f32 v[138:139], v[240:241], v[138:139], v[88:89]
	v_pk_fma_f32 v[140:141], v[242:243], v[140:141], v[90:91]
	s_add_u32 s14, s12, 0x30000
	s_addc_u32 s15, s13, 0
	global_store_dwordx4 v206, v[134:137], s[14:15]
	global_store_dwordx4 v206, v[130:133], s[14:15] offset:16
	global_store_dwordx4 v206, v[142:145], s[14:15] offset:512
	global_store_dwordx4 v206, v[138:141], s[14:15] offset:528
	s_add_u32 s40, s10, 0xa0000
	s_addc_u32 s41, s11, 0
	global_load_dwordx4 v[84:87], v206, s[40:41]
	global_load_dwordx4 v[80:83], v206, s[40:41] offset:16
	global_load_dwordx4 v[92:95], v206, s[40:41] offset:512
	global_load_dwordx4 v[88:91], v206, s[40:41] offset:528
	s_waitcnt vmcnt(16)
; #define ROW_FENCE asm volatile("" ::: "memory")
;     DI void operator()(Acc& acc, const Unit& u, int wr, int wc, int fr, int fq) const {
;     ...
;         for (int aim = 0; aim < 8; ++aim) { const int ai = aim >> 2, m = aim & 3;
;             f32x4 xa[2][2]; f32x2 sv = {0.f, 1.f};
;             if (ln) sv = *(const f32x2*)(st + 2 * (size_t)(row0 + EPI_ROWS(ai, m) + oz_));
; #pragma unroll
;             for (int bj = 0; bj < 2; ++bj) { const float* p = xib + (size_t)(EPI_ROWS(ai, m) + oz_) * D + EPI_COL8(bj); xa[bj][0] = *(const f32x4*)p; xa[bj][1] = *(const f32x4*)(p + 4); }
; #pragma unroll
;             for (int bj = 0; bj < 2; ++bj) { float* p = xob + (size_t)(EPI_ROWS(ai, m) + oz_) * D + EPI_COL8(bj);
;                 *(f32x4*)p = ((xa[bj][0] - sv[0]) * sv[1]) * la[bj][0] + acc[ai][bj][m][0];
;                 *(f32x4*)(p + 4) = ((xa[bj][1] - sv[0]) * sv[1]) * la[bj][1] + acc[ai][bj][m][1]; }
;             if (m & 1) ROW_FENCE;
;         }
	v_sub_f32_e32 v118, v118, v252
	v_sub_f32_e32 v119, v119, v252
	v_sub_f32_e32 v120, v120, v252
	v_sub_f32_e32 v121, v121, v252
	v_sub_f32_e32 v114, v114, v252
	v_sub_f32_e32 v115, v115, v252
	v_sub_f32_e32 v116, v116, v252
	v_sub_f32_e32 v117, v117, v252
	v_sub_f32_e32 v126, v126, v252
	v_sub_f32_e32 v127, v127, v252
	v_sub_f32_e32 v128, v128, v252
	v_sub_f32_e32 v129, v129, v252
	v_sub_f32_e32 v122, v122, v252
	v_sub_f32_e32 v123, v123, v252
	v_sub_f32_e32 v124, v124, v252
	v_sub_f32_e32 v125, v125, v252
	v_pk_mul_f32 v[118:119], v[252:253], v[118:119] op_sel:[1,0]
	v_pk_mul_f32 v[120:121], v[252:253], v[120:121] op_sel:[1,0]
	v_pk_mul_f32 v[114:115], v[252:253], v[114:115] op_sel:[1,0]
	v_pk_mul_f32 v[116:117], v[252:253], v[116:117] op_sel:[1,0]
	v_pk_mul_f32 v[126:127], v[252:253], v[126:127] op_sel:[1,0]
	v_pk_mul_f32 v[128:129], v[252:253], v[128:129] op_sel:[1,0]
	v_pk_mul_f32 v[122:123], v[252:253], v[122:123] op_sel:[1,0]
	v_pk_mul_f32 v[124:125], v[252:253], v[124:125] op_sel:[1,0]
	v_pk_fma_f32 v[118:119], v[228:229], v[118:119], v[52:53]
	v_pk_fma_f32 v[120:121], v[230:231], v[120:121], v[54:55]
	v_pk_fma_f32 v[114:115], v[232:233], v[114:115], v[48:49]
	v_pk_fma_f32 v[116:117], v[234:235], v[116:117], v[50:51]
	v_pk_fma_f32 v[126:127], v[236:237], v[126:127], v[60:61]
	v_pk_fma_f32 v[128:129], v[238:239], v[128:129], v[62:63]
	v_pk_fma_f32 v[122:123], v[240:241], v[122:123], v[56:57]
	v_pk_fma_f32 v[124:125], v[242:243], v[124:125], v[58:59]
	s_add_u32 s14, s12, 0x80000
	s_addc_u32 s15, s13, 0
	global_store_dwordx4 v206, v[118:121], s[14:15]
	global_store_dwordx4 v206, v[114:117], s[14:15] offset:16
	global_store_dwordx4 v206, v[126:129], s[14:15] offset:512
	global_store_dwordx4 v206, v[122:125], s[14:15] offset:528
	s_add_u32 s40, s10, 0xb0000
	s_addc_u32 s41, s11, 0
	global_load_dwordx4 v[52:55], v206, s[40:41]
	global_load_dwordx4 v[48:51], v206, s[40:41] offset:16
	global_load_dwordx4 v[60:63], v206, s[40:41] offset:512
	global_load_dwordx4 v[56:59], v206, s[40:41] offset:528
	s_waitcnt vmcnt(16)
	v_sub_f32_e32 v102, v102, v174
	v_sub_f32_e32 v103, v103, v174
	v_sub_f32_e32 v104, v104, v174
	v_sub_f32_e32 v105, v105, v174
	v_sub_f32_e32 v98, v98, v174
	v_sub_f32_e32 v99, v99, v174
	v_sub_f32_e32 v100, v100, v174
	v_sub_f32_e32 v101, v101, v174
	v_sub_f32_e32 v110, v110, v174
	v_sub_f32_e32 v111, v111, v174
	v_sub_f32_e32 v112, v112, v174
	v_sub_f32_e32 v113, v113, v174
	v_sub_f32_e32 v106, v106, v174
	v_sub_f32_e32 v107, v107, v174
	v_sub_f32_e32 v108, v108, v174
	v_sub_f32_e32 v109, v109, v174
	v_pk_mul_f32 v[102:103], v[174:175], v[102:103] op_sel:[1,0]
	v_pk_mul_f32 v[104:105], v[174:175], v[104:105] op_sel:[1,0]
	v_pk_mul_f32 v[98:99], v[174:175], v[98:99] op_sel:[1,0]
	v_pk_mul_f32 v[100:101], v[174:175], v[100:101] op_sel:[1,0]
	v_pk_mul_f32 v[110:111], v[174:175], v[110:111] op_sel:[1,0]
	v_pk_mul_f32 v[112:113], v[174:175], v[112:113] op_sel:[1,0]
	v_pk_mul_f32 v[106:107], v[174:175], v[106:107] op_sel:[1,0]
	v_pk_mul_f32 v[108:109], v[174:175], v[108:109] op_sel:[1,0]
	v_pk_fma_f32 v[102:103], v[228:229], v[102:103], v[36:37]
	v_pk_fma_f32 v[104:105], v[230:231], v[104:105], v[38:39]
	v_pk_fma_f32 v[98:99], v[232:233], v[98:99], v[32:33]
	v_pk_fma_f32 v[100:101], v[234:235], v[100:101], v[34:35]
	v_pk_fma_f32 v[110:111], v[236:237], v[110:111], v[44:45]
	v_pk_fma_f32 v[112:113], v[238:239], v[112:113], v[46:47]
	v_pk_fma_f32 v[106:107], v[240:241], v[106:107], v[40:41]
	v_pk_fma_f32 v[108:109], v[242:243], v[108:109], v[42:43]
	s_add_u32 s14, s12, 0x90000
	s_addc_u32 s15, s13, 0
	global_store_dwordx4 v206, v[102:105], s[14:15]
	global_store_dwordx4 v206, v[98:101], s[14:15] offset:16
	global_store_dwordx4 v206, v[110:113], s[14:15] offset:512
	global_store_dwordx4 v206, v[106:109], s[14:15] offset:528
	s_waitcnt vmcnt(12)
; #define ROW_FENCE asm volatile("" ::: "memory")
;     DI void operator()(Acc& acc, const Unit& u, int wr, int wc, int fr, int fq) const {
;     ...
;         for (int aim = 0; aim < 8; ++aim) { const int ai = aim >> 2, m = aim & 3;
;             f32x4 xa[2][2]; f32x2 sv = {0.f, 1.f};
;             if (ln) sv = *(const f32x2*)(st + 2 * (size_t)(row0 + EPI_ROWS(ai, m) + oz_));
; #pragma unroll
;             for (int bj = 0; bj < 2; ++bj) { const float* p = xib + (size_t)(EPI_ROWS(ai, m) + oz_) * D + EPI_COL8(bj); xa[bj][0] = *(const f32x4*)p; xa[bj][1] = *(const f32x4*)(p + 4); }
; #pragma unroll
;             for (int bj = 0; bj < 2; ++bj) { float* p = xob + (size_t)(EPI_ROWS(ai, m) + oz_) * D + EPI_COL8(bj);
;                 *(f32x4*)p = ((xa[bj][0] - sv[0]) * sv[1]) * la[bj][0] + acc[ai][bj][m][0];
;                 *(f32x4*)(p + 4) = ((xa[bj][1] - sv[0]) * sv[1]) * la[bj][1] + acc[ai][bj][m][1]; }
;             if (m & 1) ROW_FENCE;
;         }
	v_sub_f32_e32 v84, v84, v176
	v_sub_f32_e32 v85, v85, v176
	v_sub_f32_e32 v86, v86, v176
	v_sub_f32_e32 v87, v87, v176
	v_sub_f32_e32 v80, v80, v176
	v_sub_f32_e32 v81, v81, v176
	v_sub_f32_e32 v82, v82, v176
	v_sub_f32_e32 v83, v83, v176
	v_sub_f32_e32 v92, v92, v176
	v_sub_f32_e32 v93, v93, v176
	v_sub_f32_e32 v94, v94, v176
	v_sub_f32_e32 v95, v95, v176
	v_sub_f32_e32 v88, v88, v176
	v_sub_f32_e32 v89, v89, v176
	v_sub_f32_e32 v90, v90, v176
	v_sub_f32_e32 v91, v91, v176
	v_pk_mul_f32 v[84:85], v[176:177], v[84:85] op_sel:[1,0]
	v_pk_mul_f32 v[86:87], v[176:177], v[86:87] op_sel:[1,0]
	v_pk_mul_f32 v[80:81], v[176:177], v[80:81] op_sel:[1,0]
	v_pk_mul_f32 v[82:83], v[176:177], v[82:83] op_sel:[1,0]
	v_pk_mul_f32 v[92:93], v[176:177], v[92:93] op_sel:[1,0]
	v_pk_mul_f32 v[94:95], v[176:177], v[94:95] op_sel:[1,0]
	v_pk_mul_f32 v[88:89], v[176:177], v[88:89] op_sel:[1,0]
	v_pk_mul_f32 v[90:91], v[176:177], v[90:91] op_sel:[1,0]
	v_pk_fma_f32 v[84:85], v[228:229], v[84:85], v[20:21]
	v_pk_fma_f32 v[86:87], v[230:231], v[86:87], v[22:23]
	v_pk_fma_f32 v[80:81], v[232:233], v[80:81], v[16:17]
	v_pk_fma_f32 v[82:83], v[234:235], v[82:83], v[18:19]
	v_pk_fma_f32 v[92:93], v[236:237], v[92:93], v[28:29]
	v_pk_fma_f32 v[94:95], v[238:239], v[94:95], v[30:31]
	v_pk_fma_f32 v[88:89], v[240:241], v[88:89], v[24:25]
	v_pk_fma_f32 v[90:91], v[242:243], v[90:91], v[26:27]
	s_add_u32 s14, s12, 0xa0000
	s_addc_u32 s15, s13, 0
	global_store_dwordx4 v206, v[84:87], s[14:15]
	global_store_dwordx4 v206, v[80:83], s[14:15] offset:16
	global_store_dwordx4 v206, v[92:95], s[14:15] offset:512
	global_store_dwordx4 v206, v[88:91], s[14:15] offset:528
	s_waitcnt vmcnt(8)
	v_sub_f32_e32 v52, v52, v204
	v_sub_f32_e32 v53, v53, v204
	v_sub_f32_e32 v54, v54, v204
	v_sub_f32_e32 v55, v55, v204
	v_sub_f32_e32 v48, v48, v204
	v_sub_f32_e32 v49, v49, v204
	v_sub_f32_e32 v50, v50, v204
	v_sub_f32_e32 v51, v51, v204
	v_sub_f32_e32 v60, v60, v204
	v_sub_f32_e32 v61, v61, v204
	v_sub_f32_e32 v62, v62, v204
	v_sub_f32_e32 v63, v63, v204
	v_sub_f32_e32 v56, v56, v204
	v_sub_f32_e32 v57, v57, v204
	v_sub_f32_e32 v58, v58, v204
	v_sub_f32_e32 v59, v59, v204
	v_pk_mul_f32 v[52:53], v[204:205], v[52:53] op_sel:[1,0]
	v_pk_mul_f32 v[54:55], v[204:205], v[54:55] op_sel:[1,0]
	v_pk_mul_f32 v[48:49], v[204:205], v[48:49] op_sel:[1,0]
	v_pk_mul_f32 v[50:51], v[204:205], v[50:51] op_sel:[1,0]
	v_pk_mul_f32 v[60:61], v[204:205], v[60:61] op_sel:[1,0]
	v_pk_mul_f32 v[62:63], v[204:205], v[62:63] op_sel:[1,0]
	v_pk_mul_f32 v[56:57], v[204:205], v[56:57] op_sel:[1,0]
	v_pk_mul_f32 v[58:59], v[204:205], v[58:59] op_sel:[1,0]
	v_pk_fma_f32 v[52:53], v[228:229], v[52:53], v[8:9]
	v_pk_fma_f32 v[54:55], v[230:231], v[54:55], v[10:11]
	v_pk_fma_f32 v[48:49], v[232:233], v[48:49], v[4:5]
	v_pk_fma_f32 v[50:51], v[234:235], v[50:51], v[6:7]
	v_pk_fma_f32 v[60:61], v[236:237], v[60:61], v[12:13]
	v_pk_fma_f32 v[62:63], v[238:239], v[62:63], v[14:15]
	v_pk_fma_f32 v[56:57], v[240:241], v[56:57], v[0:1]
	v_pk_fma_f32 v[58:59], v[242:243], v[58:59], v[2:3]
	s_add_u32 s14, s12, 0xb0000
	s_addc_u32 s15, s13, 0
	global_store_dwordx4 v206, v[52:55], s[14:15]
	global_store_dwordx4 v206, v[48:51], s[14:15] offset:16
	global_store_dwordx4 v206, v[60:63], s[14:15] offset:512
	global_store_dwordx4 v206, v[56:59], s[14:15] offset:528
	s_mov_b64 s[4:5], -1
	s_andn2_b64 vcc, exec, s[2:3]
	s_cbranch_vccnz .LBB0_133
	v_readlane_b32 s2, v255, 51
	v_readlane_b32 s3, v255, 52
	s_andn2_b64 vcc, exec, s[2:3]
	s_cbranch_vccnz .LBB0_132
	s_barrier
	s_branch .LBB0_132
